# GEMM K-loop: loop-invariant LDS fragment base addresses hoisted to v238-v241 (4 v_add_u32 per wave-iteration removed); on top of saddr-form LDS-DMA, phase-0 nt loads, gate_up item remap
# baseline (speedup 1.0000x reference)
; #define SNEXT(i, u) sched_next(i, u, p.G, p.c, p.total, p.mode, p.nM0, p.nN0, p.A0, p.B0, p.A1, p.B1, p.A2, p.B2, p.A3, p.B3)
; #define PG8_STAGE(bufoff, gbase, voff) do { _Pragma("unroll") for (int _i = 0; _i < 2; ++_i) \
;         __builtin_amdgcn_global_load_lds((const unsigned*)((const char*)(gbase) + (voff)[_i]), (LAS unsigned*)(lds + (bufoff) + ldsw + _i * 8192), 16, 0, 0); } while (0)
; #define PG8_WAIT_V(n) asm volatile("s_waitcnt vmcnt(" #n ")" ::: "memory")
; #define PG8_BAR __builtin_amdgcn_s_barrier()
; __device__ __forceinline__ void gemm_phase(LAS unsigned char* lds, const GP p, const int tid) {
;     ...
;     const int wid = __builtin_amdgcn_readfirstlane(tid >> 6), lane = tid & 63, wr = wid >> 2, wc = wid & 3, fr = lane & 15, fq = lane >> 4;
;     const int nt = K / BK;
;     unsigned voffA[2], voffB[2];
; #pragma unroll
;     for (int i = 0; i < 2; ++i) { int R, C; stage_rc(tid * 16 + i * 8192, R, C); const int Rb = (R & ~31) + perm32(R & 31);
;         voffA[i] = (unsigned)(R * K + C) * 2u; voffB[i] = (unsigned)(Rb * K + C) * 2u; }
;     const size_t kstep = (size_t)(BK * 2);
;     const size_t hstep = (size_t)HALF * K * 2;
;     const unsigned ldsw = (unsigned)wid * 1024u;
;     const int aoff = lds_byte(wr * 64 + fr, fq * 8), boff = lds_byte(wc * 32 + fr, fq * 8);
;     ...
;     Unit cur, nxt; int ui = 0;
;     if (!SNEXT(0, cur)) return;
;     f32x4 acc[2][2][4][2];
; #pragma unroll
;     for (int a = 0; a < 2; ++a)
; #pragma unroll
;         for (int b = 0; b < 2; ++b)
; #pragma unroll
;             for (int m = 0; m < 4; ++m)
; #pragma unroll
;                 for (int n = 0; n < 2; ++n) acc[a][b][m][n] = (f32x4){0.f, 0.f, 0.f, 0.f};
;     bf16x8 At[4][2], B0[2][2], B1[2][2];
;     float rsv[2][4];
; #pragma unroll
;     for (int ai = 0; ai < 2; ++ai)
; #pragma unroll
;         for (int m = 0; m < 4; ++m) rsv[ai][m] = 1.0f;
;     const char* cA = APTR(cur); const char* cB = BPTR(cur);
;     PG8_STAGE(PG8_SB(0, 0), cB, voffB); PG8_STAGE(PG8_SB(0, 1), cB + hstep, voffB); PG8_STAGE(PG8_SA(0, 0), cA, voffA); PG8_STAGE(PG8_SA(0, 1), cA + hstep, voffA);
;     if (wr == 1) PG8_BAR;
;     PG8_WAIT_V(2); PG8_BAR;
;     PG8_STAGE(PG8_SB(1, 0), cB + kstep, voffB); PG8_STAGE(PG8_SA(1, 0), cA + kstep, voffA); PG8_STAGE(PG8_SB(1, 1), cB + hstep + kstep, voffB);
;     PG8_WAIT_V(6); PG8_BAR;
.LBB0_82:
	v_mov_b32_e32 v149, v145
	v_lshl_add_u64 v[8:9], s[84:85], 0, v[148:149]
	v_mov_b32_e32 v153, v145
	v_lshl_add_u64 v[10:11], s[84:85], 0, v[152:153]
	v_mov_b32_e32 v147, v145
	s_add_i32 m0, s53, 0x18000
	v_lshl_add_u64 v[8:9], v[8:9], 0, s[36:37]
	v_lshl_add_u64 v[16:17], s[82:83], 0, v[146:147]
	v_mov_b32_e32 v151, v145
	s_waitcnt vmcnt(2)
	s_barrier
	global_load_lds_dwordx4 v[8:9], off
	v_lshl_add_u64 v[8:9], v[10:11], 0, s[36:37]
	s_add_i32 m0, s53, 0x1a000
	s_add_i32 s57, s53, 0x8000
	v_lshl_add_u64 v[18:19], s[82:83], 0, v[150:151]
	global_load_lds_dwordx4 v[8:9], off
	v_lshl_add_u64 v[8:9], v[16:17], 0, s[36:37]
	s_mov_b32 m0, s57
	s_add_i32 s58, s53, 0xa000
	v_lshl_add_u64 v[12:13], s[8:9], 0, v[148:149]
	global_load_lds_dwordx4 v[8:9], off
	v_lshl_add_u64 v[8:9], v[18:19], 0, s[36:37]
	s_mov_b32 m0, s58
	v_lshl_add_u64 v[14:15], s[8:9], 0, v[152:153]
	global_load_lds_dwordx4 v[8:9], off
	s_add_i32 m0, s53, 0x1c000
	v_lshl_add_u64 v[8:9], v[12:13], 0, s[36:37]
	global_load_lds_dwordx4 v[8:9], off
	v_lshl_add_u64 v[8:9], v[14:15], 0, s[36:37]
	s_add_i32 m0, s53, 0x1e000
	v_and_b32_e32 v7, 15, v0
	global_load_lds_dwordx4 v[8:9], off
	v_lshrrev_b32_e32 v0, 1, v0
	v_and_b32_e32 v0, 24, v0
	s_lshl_b32 s6, s41, 6
	v_lshlrev_b32_e32 v8, 1, v0
	v_lshlrev_b32_e32 v144, 2, v7
	v_or_b32_e32 v157, s6, v7
	v_lshl_or_b32 v8, v7, 6, v8
	s_lshl_b32 s7, s41, 13
	v_and_b32_e32 v7, 32, v144
	v_bitop3_b32 v9, v8, s7, v7 bitop3:0xde
	s_lshl_b32 s7, s40, 5
	s_and_b32 s40, s7, 0x60
	s_lshl_b32 s7, s40, 7
	s_lshr_b32 s60, s42, 6
	v_bitop3_b32 v165, s7, v8, v7 bitop3:0xf6
	v_add_u32_e32 v238, 0x10000, v165
	v_add_u32_e32 v239, 0x14000, v165
	v_add_u32_e32 v240, 0x18000, v165
	v_add_u32_e32 v241, 0x1c000, v165
	s_ashr_i32 s7, s6, 31
	s_add_i32 s59, s60, -2
	s_lshl_b64 s[6:7], s[6:7], 2
	v_readlane_b32 s76, v252, 22
	v_readlane_b32 s77, v252, 23
	s_add_u32 s6, s76, s6
	s_addc_u32 s7, s77, s7
	v_or_b32_e32 v156, s40, v0
	v_lshl_add_u64 v[154:155], s[6:7], 0, v[144:145]
	v_lshlrev_b32_e32 v144, 2, v156
	v_add_u32_e32 v0, v3, v1
	s_waitcnt vmcnt(6)
	v_lshl_add_u64 v[158:159], s[76:77], 0, v[144:145]
	v_add_lshl_u32 v144, v0, v2, 1
	v_add_u32_e32 v0, v6, v4
	s_cmpk_lt_u32 s43, 0x100
	v_lshl_add_u64 v[160:161], s[74:75], 0, v[144:145]
	v_add_lshl_u32 v144, v0, v5, 1
	s_cselect_b64 s[8:9], -1, 0
	v_lshl_add_u64 v[162:163], s[74:75], 0, v[144:145]
	v_mov_b32_e32 v164, 1.0
	s_mov_b32 s61, 0
	v_add_u32_e32 v167, 0, v9
	v_mov_b32_e32 v166, 1.0
	v_mov_b32_e32 v168, 1.0
	v_mov_b32_e32 v170, 1.0
	v_mov_b32_e32 v172, 1.0
	v_mov_b32_e32 v174, 1.0
	v_mov_b32_e32 v176, 1.0
	v_mov_b32_e32 v178, 1.0
	s_barrier
	s_branch .LBB0_85

; #define PG8_STAGE(bufoff, gbase, voff) do { _Pragma("unroll") for (int _i = 0; _i < 2; ++_i) \
;         __builtin_amdgcn_global_load_lds((const unsigned*)((const char*)(gbase) + (voff)[_i]), (LAS unsigned*)(lds + (bufoff) + ldsw + _i * 8192), 16, 0, 0); } while (0)
; #define PG8_LDA(dst, b, h) do { _Pragma("unroll") for (int m = 0; m < 4; ++m) _Pragma("unroll") for (int k = 0; k < 2; ++k) dst[m][k] = *(const LAS bf16x8*)(lds + PG8_SA(b, h) + aoff + m * 2048 + k * 1024); } while (0)
; #define PG8_LDB(dst, b, h) do { _Pragma("unroll") for (int n = 0; n < 2; ++n) _Pragma("unroll") for (int k = 0; k < 2; ++k) dst[n][k] = *(const LAS bf16x8*)(lds + PG8_SB(b, h) + boff + n * 2048 + k * 1024); } while (0)
; #define PG8_MMA(ai, bj, At, Bt) do { __builtin_amdgcn_s_setprio(1); _Pragma("unroll") for (int m = 0; m < 4; ++m) _Pragma("unroll") for (int n = 0; n < 2; ++n) _Pragma("unroll") for (int k = 0; k < 2; ++k) \
;         acc[ai][bj][m][n] = __builtin_amdgcn_mfma_f32_16x16x32_bf16(Bt[n][k], At[m][k], acc[ai][bj][m][n], 0, 0, 0); __builtin_amdgcn_s_setprio(0); } while (0)
; #define PG8_WAIT_V(n) asm volatile("s_waitcnt vmcnt(" #n ")" ::: "memory")
; #define PG8_WAIT_L(n) asm volatile("s_waitcnt lgkmcnt(" #n ")" ::: "memory")
; #define PG8_BAR __builtin_amdgcn_s_barrier()
; #define PG8_SCHED __builtin_amdgcn_sched_barrier(0)
; __device__ __forceinline__ void gemm_phase(LAS unsigned char* lds, const GP p, const int tid) {
;     ...
;             PG8_LDB(B0, 0, 0); PG8_LDB(B1, 0, 1); PG8_SCHED; PG8_LDA(At, 0, 0); PG8_STAGE(PG8_SA(1, 1), a1 + hstep, voffA);
;             PG8_WAIT_V(8); PG8_WAIT_L(0); PG8_BAR; PG8_MMA(0, 0, At, B0); PG8_MMA(0, 1, At, B1); PG8_BAR; PG8_SCHED;
;             PG8_LDA(At, 0, 1); PG8_STAGE(PG8_SB(0, 0), b2, voffB); PG8_STAGE(PG8_SB(0, 1), b2 + hstep, voffB); PG8_STAGE(PG8_SA(0, 0), a2, voffA);
;             PG8_WAIT_V(8); PG8_WAIT_L(0); PG8_BAR; PG8_MMA(1, 0, At, B0); PG8_MMA(1, 1, At, B1); PG8_BAR; PG8_SCHED;
.LBB0_104:
	s_add_i32 s98, s98, 2
	s_add_u32 s43, s82, 0x80
	s_addc_u32 s99, s83, 0
	s_and_b64 s[86:87], s[84:85], exec
	s_cselect_b32 s87, s77, s99
	s_cselect_b32 s86, s76, s43
	s_add_i32 s43, 0, 0x10000
	s_and_b64 s[84:85], s[84:85], exec
	s_cselect_b32 s85, s79, s91
	s_cselect_b32 s84, s78, s81
	s_add_i32 s99, 0, 0x14000
	ds_read_b128 v[130:133], v238
	ds_read_b128 v[134:137], v238 offset:1024
	ds_read_b128 v[138:141], v238 offset:2048
	ds_read_b128 v[180:183], v238 offset:3072
	ds_read_b128 v[184:187], v239
	ds_read_b128 v[188:191], v239 offset:1024
	ds_read_b128 v[192:195], v239 offset:2048
	ds_read_b128 v[196:199], v239 offset:3072
	s_add_i32 m0, s53, 0xc000
	ds_read_b128 v[200:203], v167
	ds_read_b128 v[204:207], v167 offset:1024
	ds_read_b128 v[208:211], v167 offset:2048
	ds_read_b128 v[218:221], v167 offset:3072
	ds_read_b128 v[222:225], v167 offset:4096
	ds_read_b128 v[226:229], v167 offset:5120
	ds_read_b128 v[230:233], v167 offset:6144
	ds_read_b128 v[234:237], v167 offset:7168
	global_load_lds_dwordx4 v160, s[82:83]
	s_add_i32 m0, s53, 0xe000
	s_nop 0
	global_load_lds_dwordx4 v162, s[82:83]
	s_waitcnt vmcnt(8)
	s_waitcnt lgkmcnt(0)
	s_barrier
	s_setprio 1
	s_waitcnt lgkmcnt(0)
	v_mfma_f32_16x16x32_bf16 v[124:127], v[130:133], v[200:203], v[124:127]
	v_mfma_f32_16x16x32_bf16 v[120:123], v[138:141], v[200:203], v[120:123]
	v_mfma_f32_16x16x32_bf16 v[108:111], v[130:133], v[208:211], v[108:111]
	v_mfma_f32_16x16x32_bf16 v[104:107], v[138:141], v[208:211], v[104:107]
	v_mfma_f32_16x16x32_bf16 v[92:95], v[130:133], v[222:225], v[92:95]
	v_mfma_f32_16x16x32_bf16 v[88:91], v[138:141], v[222:225], v[88:91]
	v_mfma_f32_16x16x32_bf16 v[76:79], v[130:133], v[230:233], v[76:79]
	v_mfma_f32_16x16x32_bf16 v[72:75], v[138:141], v[230:233], v[72:75]
	v_mfma_f32_16x16x32_bf16 v[124:127], v[134:137], v[204:207], v[124:127]
	v_mfma_f32_16x16x32_bf16 v[120:123], v[180:183], v[204:207], v[120:123]
	v_mfma_f32_16x16x32_bf16 v[108:111], v[134:137], v[218:221], v[108:111]
	v_mfma_f32_16x16x32_bf16 v[104:107], v[180:183], v[218:221], v[104:107]
	v_mfma_f32_16x16x32_bf16 v[92:95], v[134:137], v[226:229], v[92:95]
	v_mfma_f32_16x16x32_bf16 v[88:91], v[180:183], v[226:229], v[88:91]
	v_mfma_f32_16x16x32_bf16 v[76:79], v[134:137], v[234:237], v[76:79]
	v_mfma_f32_16x16x32_bf16 v[72:75], v[180:183], v[234:237], v[72:75]
	s_setprio 0
	s_setprio 1
	v_mfma_f32_16x16x32_bf16 v[116:119], v[184:187], v[200:203], v[116:119]
	v_mfma_f32_16x16x32_bf16 v[112:115], v[192:195], v[200:203], v[112:115]
	v_mfma_f32_16x16x32_bf16 v[100:103], v[184:187], v[208:211], v[100:103]
	v_mfma_f32_16x16x32_bf16 v[96:99], v[192:195], v[208:211], v[96:99]
	v_mfma_f32_16x16x32_bf16 v[84:87], v[184:187], v[222:225], v[84:87]
	v_mfma_f32_16x16x32_bf16 v[80:83], v[192:195], v[222:225], v[80:83]
	v_mfma_f32_16x16x32_bf16 v[68:71], v[184:187], v[230:233], v[68:71]
	v_mfma_f32_16x16x32_bf16 v[64:67], v[192:195], v[230:233], v[64:67]
	v_mfma_f32_16x16x32_bf16 v[116:119], v[188:191], v[204:207], v[116:119]
	v_mfma_f32_16x16x32_bf16 v[112:115], v[196:199], v[204:207], v[112:115]
	v_mfma_f32_16x16x32_bf16 v[100:103], v[188:191], v[218:221], v[100:103]
	v_mfma_f32_16x16x32_bf16 v[96:99], v[196:199], v[218:221], v[96:99]
	v_mfma_f32_16x16x32_bf16 v[84:87], v[188:191], v[226:229], v[84:87]
	v_mfma_f32_16x16x32_bf16 v[80:83], v[196:199], v[226:229], v[80:83]
	v_mfma_f32_16x16x32_bf16 v[68:71], v[188:191], v[234:237], v[68:71]
	v_mfma_f32_16x16x32_bf16 v[64:67], v[196:199], v[234:237], v[64:67]
	s_setprio 0
	s_barrier
	s_add_i32 s43, s43, s52
	s_mov_b64 s[100:101], s[84:85]
	s_mov_b32 m0, s43
	ds_read_b128 v[200:203], v167 offset:16384
	ds_read_b128 v[204:207], v167 offset:17408
	ds_read_b128 v[208:211], v167 offset:18432
	ds_read_b128 v[218:221], v167 offset:19456
	ds_read_b128 v[222:225], v167 offset:20480
	ds_read_b128 v[226:229], v167 offset:21504
	ds_read_b128 v[230:233], v167 offset:22528
	ds_read_b128 v[234:237], v167 offset:23552
	global_load_lds_dwordx4 v148, s[84:85]
	s_add_i32 m0, s43, 0x2000
	s_add_i32 s43, s99, s52
	global_load_lds_dwordx4 v152, s[84:85]
	s_add_u32 s84, s84, s74
	s_addc_u32 s85, s85, 0
	s_mov_b32 m0, s43
	s_nop 0
	global_load_lds_dwordx4 v148, s[84:85]
	s_add_i32 m0, s43, 0x2000
	s_nop 0
	global_load_lds_dwordx4 v152, s[84:85]
	s_mov_b32 m0, s53
	s_nop 0
	global_load_lds_dwordx4 v146, s[86:87]
	s_mov_b32 m0, s54
	s_nop 0
	global_load_lds_dwordx4 v150, s[86:87]
	s_waitcnt vmcnt(8)
	s_waitcnt lgkmcnt(0)
	s_barrier
	s_setprio 1
	s_waitcnt lgkmcnt(0)
	v_mfma_f32_16x16x32_bf16 v[60:63], v[130:133], v[200:203], v[60:63]
	v_mfma_f32_16x16x32_bf16 v[56:59], v[138:141], v[200:203], v[56:59]
	v_mfma_f32_16x16x32_bf16 v[44:47], v[130:133], v[208:211], v[44:47]
	v_mfma_f32_16x16x32_bf16 v[40:43], v[138:141], v[208:211], v[40:43]
	v_mfma_f32_16x16x32_bf16 v[28:31], v[130:133], v[222:225], v[28:31]
	v_mfma_f32_16x16x32_bf16 v[24:27], v[138:141], v[222:225], v[24:27]
	v_mfma_f32_16x16x32_bf16 v[12:15], v[130:133], v[230:233], v[12:15]
	v_mfma_f32_16x16x32_bf16 v[8:11], v[138:141], v[230:233], v[8:11]
	v_mfma_f32_16x16x32_bf16 v[60:63], v[134:137], v[204:207], v[60:63]
	v_mfma_f32_16x16x32_bf16 v[56:59], v[180:183], v[204:207], v[56:59]
	v_mfma_f32_16x16x32_bf16 v[44:47], v[134:137], v[218:221], v[44:47]
	v_mfma_f32_16x16x32_bf16 v[40:43], v[180:183], v[218:221], v[40:43]
	v_mfma_f32_16x16x32_bf16 v[28:31], v[134:137], v[226:229], v[28:31]
	v_mfma_f32_16x16x32_bf16 v[24:27], v[180:183], v[226:229], v[24:27]
	v_mfma_f32_16x16x32_bf16 v[12:15], v[134:137], v[234:237], v[12:15]
	v_mfma_f32_16x16x32_bf16 v[8:11], v[180:183], v[234:237], v[8:11]
	s_setprio 0
	s_setprio 1
	v_mfma_f32_16x16x32_bf16 v[52:55], v[184:187], v[200:203], v[52:55]
	v_mfma_f32_16x16x32_bf16 v[48:51], v[192:195], v[200:203], v[48:51]
	v_mfma_f32_16x16x32_bf16 v[36:39], v[184:187], v[208:211], v[36:39]
	v_mfma_f32_16x16x32_bf16 v[32:35], v[192:195], v[208:211], v[32:35]
	v_mfma_f32_16x16x32_bf16 v[20:23], v[184:187], v[222:225], v[20:23]
	v_mfma_f32_16x16x32_bf16 v[16:19], v[192:195], v[222:225], v[16:19]
	v_mfma_f32_16x16x32_bf16 v[4:7], v[184:187], v[230:233], v[4:7]
	v_mfma_f32_16x16x32_bf16 v[0:3], v[192:195], v[230:233], v[0:3]
	v_mfma_f32_16x16x32_bf16 v[52:55], v[188:191], v[204:207], v[52:55]
	v_mfma_f32_16x16x32_bf16 v[48:51], v[196:199], v[204:207], v[48:51]
	v_mfma_f32_16x16x32_bf16 v[36:39], v[188:191], v[218:221], v[36:39]
	v_mfma_f32_16x16x32_bf16 v[32:35], v[196:199], v[218:221], v[32:35]
	v_mfma_f32_16x16x32_bf16 v[20:23], v[188:191], v[226:229], v[20:23]
	v_mfma_f32_16x16x32_bf16 v[16:19], v[196:199], v[226:229], v[16:19]
	v_mfma_f32_16x16x32_bf16 v[4:7], v[188:191], v[234:237], v[4:7]
	v_mfma_f32_16x16x32_bf16 v[0:3], v[196:199], v[234:237], v[0:3]
	s_setprio 0
	s_barrier
; #define PG8_STAGE(bufoff, gbase, voff) do { _Pragma("unroll") for (int _i = 0; _i < 2; ++_i) \
;         __builtin_amdgcn_global_load_lds((const unsigned*)((const char*)(gbase) + (voff)[_i]), (LAS unsigned*)(lds + (bufoff) + ldsw + _i * 8192), 16, 0, 0); } while (0)
; #define PG8_LDA(dst, b, h) do { _Pragma("unroll") for (int m = 0; m < 4; ++m) _Pragma("unroll") for (int k = 0; k < 2; ++k) dst[m][k] = *(const LAS bf16x8*)(lds + PG8_SA(b, h) + aoff + m * 2048 + k * 1024); } while (0)
; #define PG8_LDB(dst, b, h) do { _Pragma("unroll") for (int n = 0; n < 2; ++n) _Pragma("unroll") for (int k = 0; k < 2; ++k) dst[n][k] = *(const LAS bf16x8*)(lds + PG8_SB(b, h) + boff + n * 2048 + k * 1024); } while (0)
; #define PG8_MMA(ai, bj, At, Bt) do { __builtin_amdgcn_s_setprio(1); _Pragma("unroll") for (int m = 0; m < 4; ++m) _Pragma("unroll") for (int n = 0; n < 2; ++n) _Pragma("unroll") for (int k = 0; k < 2; ++k) \
;         acc[ai][bj][m][n] = __builtin_amdgcn_mfma_f32_16x16x32_bf16(Bt[n][k], At[m][k], acc[ai][bj][m][n], 0, 0, 0); __builtin_amdgcn_s_setprio(0); } while (0)
; #define PG8_WAIT_V(n) asm volatile("s_waitcnt vmcnt(" #n ")" ::: "memory")
; #define PG8_WAIT_L(n) asm volatile("s_waitcnt lgkmcnt(" #n ")" ::: "memory")
; #define PG8_BAR __builtin_amdgcn_s_barrier()
; #define PG8_SCHED __builtin_amdgcn_sched_barrier(0)
; __device__ __forceinline__ void gemm_phase(LAS unsigned char* lds, const GP p, const int tid) {
;     ...
;             PG8_LDB(B0, 1, 0); PG8_LDB(B1, 1, 1); PG8_SCHED; PG8_LDA(At, 1, 0); PG8_STAGE(PG8_SA(0, 1), a2 + hstep, voffA);
;             PG8_WAIT_V(8); PG8_WAIT_L(0); PG8_BAR; PG8_MMA(0, 0, At, B0); PG8_MMA(0, 1, At, B1); PG8_BAR; PG8_SCHED;
;             PG8_LDA(At, 1, 1); PG8_STAGE(PG8_SB(1, 0), b3, voffB); PG8_STAGE(PG8_SB(1, 1), b3 + hstep, voffB); PG8_STAGE(PG8_SA(1, 0), a3, voffA);
;             PG8_WAIT_V(8); PG8_WAIT_L(0); PG8_BAR; PG8_MMA(1, 0, At, B0); PG8_MMA(1, 1, At, B1); PG8_BAR; PG8_SCHED;
	s_add_i32 s43, 0, 0x18000
	s_add_i32 s99, 0, 0x1c000
	ds_read_b128 v[130:133], v240
	ds_read_b128 v[134:137], v240 offset:1024
	ds_read_b128 v[138:141], v240 offset:2048
	ds_read_b128 v[180:183], v240 offset:3072
	ds_read_b128 v[184:187], v241
	ds_read_b128 v[188:191], v241 offset:1024
	ds_read_b128 v[192:195], v241 offset:2048
	ds_read_b128 v[196:199], v241 offset:3072
	s_add_u32 s84, s86, s74
	s_addc_u32 s85, s87, 0
	s_mov_b32 m0, s55
	ds_read_b128 v[200:203], v167 offset:32768
	ds_read_b128 v[204:207], v167 offset:33792
	ds_read_b128 v[208:211], v167 offset:34816
	ds_read_b128 v[218:221], v167 offset:35840
	ds_read_b128 v[222:225], v167 offset:36864
	ds_read_b128 v[226:229], v167 offset:37888
	ds_read_b128 v[230:233], v167 offset:38912
	ds_read_b128 v[234:237], v167 offset:39936
	global_load_lds_dwordx4 v146, s[84:85]
	s_mov_b32 m0, s56
	s_nop 0
	global_load_lds_dwordx4 v150, s[84:85]
	s_waitcnt vmcnt(8)
	s_waitcnt lgkmcnt(0)
	s_barrier
	s_setprio 1
	s_waitcnt lgkmcnt(0)
	v_mfma_f32_16x16x32_bf16 v[124:127], v[130:133], v[200:203], v[124:127]
	v_mfma_f32_16x16x32_bf16 v[120:123], v[138:141], v[200:203], v[120:123]
	v_mfma_f32_16x16x32_bf16 v[108:111], v[130:133], v[208:211], v[108:111]
	v_mfma_f32_16x16x32_bf16 v[104:107], v[138:141], v[208:211], v[104:107]
	v_mfma_f32_16x16x32_bf16 v[92:95], v[130:133], v[222:225], v[92:95]
	v_mfma_f32_16x16x32_bf16 v[88:91], v[138:141], v[222:225], v[88:91]
	v_mfma_f32_16x16x32_bf16 v[76:79], v[130:133], v[230:233], v[76:79]
	v_mfma_f32_16x16x32_bf16 v[72:75], v[138:141], v[230:233], v[72:75]
	v_mfma_f32_16x16x32_bf16 v[124:127], v[134:137], v[204:207], v[124:127]
	v_mfma_f32_16x16x32_bf16 v[120:123], v[180:183], v[204:207], v[120:123]
	v_mfma_f32_16x16x32_bf16 v[108:111], v[134:137], v[218:221], v[108:111]
	v_mfma_f32_16x16x32_bf16 v[104:107], v[180:183], v[218:221], v[104:107]
	v_mfma_f32_16x16x32_bf16 v[92:95], v[134:137], v[226:229], v[92:95]
	v_mfma_f32_16x16x32_bf16 v[88:91], v[180:183], v[226:229], v[88:91]
	v_mfma_f32_16x16x32_bf16 v[76:79], v[134:137], v[234:237], v[76:79]
	v_mfma_f32_16x16x32_bf16 v[72:75], v[180:183], v[234:237], v[72:75]
	s_setprio 0
	s_setprio 1
	v_mfma_f32_16x16x32_bf16 v[116:119], v[184:187], v[200:203], v[116:119]
	v_mfma_f32_16x16x32_bf16 v[112:115], v[192:195], v[200:203], v[112:115]
	v_mfma_f32_16x16x32_bf16 v[100:103], v[184:187], v[208:211], v[100:103]
	v_mfma_f32_16x16x32_bf16 v[96:99], v[192:195], v[208:211], v[96:99]
	v_mfma_f32_16x16x32_bf16 v[84:87], v[184:187], v[222:225], v[84:87]
	v_mfma_f32_16x16x32_bf16 v[80:83], v[192:195], v[222:225], v[80:83]
	v_mfma_f32_16x16x32_bf16 v[68:71], v[184:187], v[230:233], v[68:71]
	v_mfma_f32_16x16x32_bf16 v[64:67], v[192:195], v[230:233], v[64:67]
	v_mfma_f32_16x16x32_bf16 v[116:119], v[188:191], v[204:207], v[116:119]
	v_mfma_f32_16x16x32_bf16 v[112:115], v[196:199], v[204:207], v[112:115]
	v_mfma_f32_16x16x32_bf16 v[100:103], v[188:191], v[218:221], v[100:103]
	v_mfma_f32_16x16x32_bf16 v[96:99], v[196:199], v[218:221], v[96:99]
	v_mfma_f32_16x16x32_bf16 v[84:87], v[188:191], v[226:229], v[84:87]
	v_mfma_f32_16x16x32_bf16 v[80:83], v[196:199], v[226:229], v[80:83]
	v_mfma_f32_16x16x32_bf16 v[68:71], v[188:191], v[234:237], v[68:71]
	v_mfma_f32_16x16x32_bf16 v[64:67], v[196:199], v[234:237], v[64:67]
	s_setprio 0
	s_barrier
	s_add_i32 s43, s43, s52
	s_add_u32 s100, s100, 0x80
	s_addc_u32 s101, s101, 0
	s_mov_b32 m0, s43
	ds_read_b128 v[200:203], v167 offset:49152
	ds_read_b128 v[204:207], v167 offset:50176
	ds_read_b128 v[208:211], v167 offset:51200
	ds_read_b128 v[218:221], v167 offset:52224
	ds_read_b128 v[222:225], v167 offset:53248
	ds_read_b128 v[226:229], v167 offset:54272
	ds_read_b128 v[230:233], v167 offset:55296
	ds_read_b128 v[234:237], v167 offset:56320
	global_load_lds_dwordx4 v148, s[100:101]
	s_add_i32 m0, s43, 0x2000
	s_add_i32 s43, s99, s52
	global_load_lds_dwordx4 v152, s[100:101]
	s_add_u32 s100, s100, s74
	s_addc_u32 s101, s101, 0
	s_mov_b32 m0, s43
	s_nop 0
	global_load_lds_dwordx4 v148, s[100:101]
	s_add_u32 s86, s86, 0x80
	s_addc_u32 s87, s87, 0
	s_add_i32 m0, s43, 0x2000
	s_nop 0
	global_load_lds_dwordx4 v152, s[100:101]
	s_mov_b32 m0, s57
	s_nop 0
	global_load_lds_dwordx4 v146, s[86:87]
	s_mov_b32 m0, s58
	s_nop 0
	global_load_lds_dwordx4 v150, s[86:87]
	s_waitcnt vmcnt(8)
	s_waitcnt lgkmcnt(0)
	s_barrier
	s_setprio 1
	s_waitcnt lgkmcnt(0)
	v_mfma_f32_16x16x32_bf16 v[60:63], v[130:133], v[200:203], v[60:63]
	v_mfma_f32_16x16x32_bf16 v[56:59], v[138:141], v[200:203], v[56:59]
	v_mfma_f32_16x16x32_bf16 v[44:47], v[130:133], v[208:211], v[44:47]
	v_mfma_f32_16x16x32_bf16 v[40:43], v[138:141], v[208:211], v[40:43]
	v_mfma_f32_16x16x32_bf16 v[28:31], v[130:133], v[222:225], v[28:31]
	v_mfma_f32_16x16x32_bf16 v[24:27], v[138:141], v[222:225], v[24:27]
	v_mfma_f32_16x16x32_bf16 v[12:15], v[130:133], v[230:233], v[12:15]
	v_mfma_f32_16x16x32_bf16 v[8:11], v[138:141], v[230:233], v[8:11]
	v_mfma_f32_16x16x32_bf16 v[60:63], v[134:137], v[204:207], v[60:63]
	v_mfma_f32_16x16x32_bf16 v[56:59], v[180:183], v[204:207], v[56:59]
	v_mfma_f32_16x16x32_bf16 v[44:47], v[134:137], v[218:221], v[44:47]
	v_mfma_f32_16x16x32_bf16 v[40:43], v[180:183], v[218:221], v[40:43]
	v_mfma_f32_16x16x32_bf16 v[28:31], v[134:137], v[226:229], v[28:31]
	v_mfma_f32_16x16x32_bf16 v[24:27], v[180:183], v[226:229], v[24:27]
	v_mfma_f32_16x16x32_bf16 v[12:15], v[134:137], v[234:237], v[12:15]
	v_mfma_f32_16x16x32_bf16 v[8:11], v[180:183], v[234:237], v[8:11]
	s_setprio 0
	s_setprio 1
	v_mfma_f32_16x16x32_bf16 v[52:55], v[184:187], v[200:203], v[52:55]
	v_mfma_f32_16x16x32_bf16 v[48:51], v[192:195], v[200:203], v[48:51]
	v_mfma_f32_16x16x32_bf16 v[36:39], v[184:187], v[208:211], v[36:39]
	v_mfma_f32_16x16x32_bf16 v[32:35], v[192:195], v[208:211], v[32:35]
	v_mfma_f32_16x16x32_bf16 v[20:23], v[184:187], v[222:225], v[20:23]
	v_mfma_f32_16x16x32_bf16 v[16:19], v[192:195], v[222:225], v[16:19]
	v_mfma_f32_16x16x32_bf16 v[4:7], v[184:187], v[230:233], v[4:7]
	v_mfma_f32_16x16x32_bf16 v[0:3], v[192:195], v[230:233], v[0:3]
	v_mfma_f32_16x16x32_bf16 v[52:55], v[188:191], v[204:207], v[52:55]
	v_mfma_f32_16x16x32_bf16 v[48:51], v[196:199], v[204:207], v[48:51]
	v_mfma_f32_16x16x32_bf16 v[36:39], v[188:191], v[218:221], v[36:39]
	v_mfma_f32_16x16x32_bf16 v[32:35], v[196:199], v[218:221], v[32:35]
	v_mfma_f32_16x16x32_bf16 v[20:23], v[188:191], v[226:229], v[20:23]
	v_mfma_f32_16x16x32_bf16 v[16:19], v[196:199], v[226:229], v[16:19]
	v_mfma_f32_16x16x32_bf16 v[4:7], v[188:191], v[234:237], v[4:7]
	v_mfma_f32_16x16x32_bf16 v[0:3], v[196:199], v[234:237], v[0:3]
	s_setprio 0
	s_barrier
	s_add_u32 s82, s82, 0x100
	s_addc_u32 s83, s83, 0
	s_add_u32 s81, s81, 0x100
	s_addc_u32 s91, s91, 0
	s_cmp_ge_u32 s98, s60
	s_cbranch_scc1 .LBB0_107
